# e13+e14: fast wo2_convert and dm_gen relocated beside P7's 12th round on 96 idle WGs
# baseline (speedup 1.0000x reference)
.Le14_rd:
	s_waitcnt lgkmcnt(0)
	s_sub_i32 s4, 0, s1
	ds_read2_b32 v[6:7], v41 offset1:33
	s_add_i32 s4, s4, s9
	s_waitcnt lgkmcnt(0)
	v_cvt_pk_bf16_f32 v48, v6, v7
	ds_read2_b32 v[6:7], v41 offset0:66 offset1:99
	v_add_u32_e32 v54, s4, v40
	s_waitcnt lgkmcnt(0)
	v_cvt_pk_bf16_f32 v49, v6, v7
	ds_read2_b32 v[6:7], v41 offset0:132 offset1:165
	s_ashr_i32 s1, s0, 31
	v_ashrrev_i32_e32 v55, 31, v54
	s_waitcnt lgkmcnt(0)
	v_cvt_pk_bf16_f32 v50, v6, v7
	ds_read2_b32 v[6:7], v41 offset0:198 offset1:231
	v_lshl_add_u64 v[52:53], s[0:1], 1, v[4:5]
	v_lshlrev_b64 v[56:57], 13, v[54:55]
	s_waitcnt lgkmcnt(0)
	v_cvt_pk_bf16_f32 v51, v6, v7
	ds_read2_b32 v[6:7], v41 offset0:8 offset1:41
	v_lshl_add_u64 v[56:57], v[52:53], 0, v[56:57]
	global_store_dwordx4 v[56:57], v[48:51], off
	v_add_u32_e32 v56, 8, v54
	v_ashrrev_i32_e32 v57, 31, v56
	s_waitcnt lgkmcnt(0)
	v_cvt_pk_bf16_f32 v48, v6, v7
	ds_read2_b32 v[6:7], v41 offset0:74 offset1:107
	s_waitcnt lgkmcnt(0)
	v_cvt_pk_bf16_f32 v49, v6, v7
	ds_read2_b32 v[6:7], v41 offset0:140 offset1:173
	s_waitcnt lgkmcnt(0)
	v_cvt_pk_bf16_f32 v50, v6, v7
	ds_read2_b32 v[6:7], v41 offset0:206 offset1:239
	v_lshlrev_b64 v[56:57], 13, v[56:57]
	s_waitcnt lgkmcnt(0)
	v_cvt_pk_bf16_f32 v51, v6, v7
	ds_read2_b32 v[6:7], v41 offset0:16 offset1:49
	v_lshl_add_u64 v[56:57], v[52:53], 0, v[56:57]
	global_store_dwordx4 v[56:57], v[48:51], off
	v_add_u32_e32 v56, 16, v54
	v_ashrrev_i32_e32 v57, 31, v56
	s_waitcnt lgkmcnt(0)
	v_cvt_pk_bf16_f32 v48, v6, v7
	ds_read2_b32 v[6:7], v41 offset0:82 offset1:115
	s_waitcnt lgkmcnt(0)
	v_cvt_pk_bf16_f32 v49, v6, v7
	ds_read2_b32 v[6:7], v41 offset0:148 offset1:181
	s_waitcnt lgkmcnt(0)
	v_cvt_pk_bf16_f32 v50, v6, v7
	ds_read2_b32 v[6:7], v41 offset0:214 offset1:247
	v_lshlrev_b64 v[56:57], 13, v[56:57]
	v_add_u32_e32 v54, 24, v54
	s_waitcnt lgkmcnt(0)
	v_cvt_pk_bf16_f32 v51, v6, v7
	ds_read2_b32 v[6:7], v41 offset0:24 offset1:57
	v_lshl_add_u64 v[56:57], v[52:53], 0, v[56:57]
	v_ashrrev_i32_e32 v55, 31, v54
	global_store_dwordx4 v[56:57], v[48:51], off
	v_lshlrev_b64 v[54:55], 13, v[54:55]
	v_lshl_add_u64 v[52:53], v[52:53], 0, v[54:55]
	s_waitcnt lgkmcnt(0)
	v_cvt_pk_bf16_f32 v48, v6, v7
	ds_read2_b32 v[6:7], v41 offset0:90 offset1:123
	s_waitcnt lgkmcnt(0)
	v_cvt_pk_bf16_f32 v49, v6, v7
	ds_read2_b32 v[6:7], v41 offset0:156 offset1:189
	s_waitcnt lgkmcnt(0)
	v_cvt_pk_bf16_f32 v50, v6, v7
	ds_read2_b32 v[6:7], v41 offset0:222 offset1:255
	s_waitcnt lgkmcnt(0)
	v_cvt_pk_bf16_f32 v51, v6, v7
	global_store_dwordx4 v[52:53], v[48:51], off
	s_waitcnt lgkmcnt(0)
	s_add_i32 s0, s8, 0x300
	v_add_u32_e32 v40, 0x6000, v40
	v_add_u32_e32 v1, 0x6000, v1
	s_cmpk_lt_i32 s8, 0x1d00
	s_mov_b32 s8, s0
	s_cbranch_scc0 .LBB0_1408
